# e36: e33 + P2 ctx item de-serialised: both K rounds' loads issued up front (second round into free VGPRs), counted waits
# speedup vs baseline: 1.0050x; 1.0050x over previous
; #define LAS __attribute__((address_space(3)))
; #define MFMA32(a, b, c) __builtin_amdgcn_mfma_f32_32x32x16_bf16(a, b, c, 0, 0, 0)
; #define MFMA32(a, b, c) __builtin_amdgcn_mfma_f32_32x32x16_f16(a, b, c, 0, 0, 0)
; __device__ __forceinline__ void ctx_item(LAS float* L, int item, const f16* hc, const f16* Wssm, f16* X) {
;     const int tid = threadIdx.x, wave = tid >> 6, lane = tid & 63, rb = item >> 4, cb = item & 15, k0 = wave * 256 + 8 * (lane >> 5);
;     const f16* ap = hc + (size_t)(rb * 32 + (lane & 31)) * D + k0;
;     const f16* bp0 = Wssm + (size_t)(cb * 64 + (lane & 31)) * D + k0; const f16* bp1 = bp0 + (size_t)32 * D;
;     f32x16 acc0, acc1;
; #pragma unroll
;     for (int i = 0; i < 16; ++i) { acc0[i] = 0.f; acc1[i] = 0.f; }
; #pragma unroll 1
;     for (int kb = 0; kb < 16; kb += 8) { f16x8 av[8], b0[8], b1[8];
; #pragma unroll
;         for (int k = 0; k < 8; ++k) { av[k] = *(const f16x8*)(ap + (kb + k) * 16); b0[k] = *(const f16x8*)(bp0 + (kb + k) * 16); b1[k] = *(const f16x8*)(bp1 + (kb + k) * 16); }
;         __builtin_amdgcn_sched_barrier(0);
; #pragma unroll
;         for (int k = 0; k < 8; ++k) { acc0 = MFMA32(av[k], b0[k], acc0); acc1 = MFMA32(av[k], b1[k], acc1); } }
.LBB0_434:
	s_lshl_b64 s[14:15], s[2:3], 1
	v_lshl_add_u64 v[136:137], v[50:51], 0, s[14:15]
	v_lshl_add_u64 v[144:145], v[48:49], 0, s[14:15]
	v_lshl_add_u64 v[84:85], v[52:53], 0, s[14:15]
	s_or_b32 s14, s2, 16
	s_mov_b32 s15, s3
	v_lshl_add_u64 v[86:87], s[14:15], 1, v[52:53]
	s_or_b32 s14, s2, 32
	v_lshl_add_u64 v[108:109], s[14:15], 1, v[52:53]
	s_or_b32 s14, s2, 48
	v_lshl_add_u64 v[110:111], s[14:15], 1, v[52:53]
	s_or_b32 s14, s2, 64
	v_lshl_add_u64 v[124:125], s[14:15], 1, v[52:53]
	s_or_b32 s14, s2, 0x50
	v_lshl_add_u64 v[128:129], s[14:15], 1, v[52:53]
	global_load_dwordx4 v[60:63], v[136:137], off
	global_load_dwordx4 v[64:67], v[136:137], off offset:32
	global_load_dwordx4 v[68:71], v[144:145], off
	global_load_dwordx4 v[72:75], v[144:145], off offset:32
	global_load_dwordx4 v[76:79], v[84:85], off
	global_load_dwordx4 v[80:83], v[86:87], off
	s_nop 0
	global_load_dwordx4 v[84:87], v[136:137], off offset:64
	global_load_dwordx4 v[88:91], v[136:137], off offset:96
	global_load_dwordx4 v[92:95], v[144:145], off offset:64
	global_load_dwordx4 v[96:99], v[144:145], off offset:96
	global_load_dwordx4 v[100:103], v[108:109], off
	global_load_dwordx4 v[104:107], v[110:111], off
	s_nop 0
	global_load_dwordx4 v[108:111], v[136:137], off offset:128
	global_load_dwordx4 v[112:115], v[136:137], off offset:160
	global_load_dwordx4 v[116:119], v[144:145], off offset:128
	global_load_dwordx4 v[120:123], v[144:145], off offset:160
	s_nop 0
	global_load_dwordx4 v[124:127], v[124:125], off
	s_nop 0
	global_load_dwordx4 v[128:131], v[128:129], off
	s_or_b32 s14, s2, 0x60
	s_or_b32 s2, s2, 0x70
	global_load_dwordx4 v[132:135], v[136:137], off offset:192
	s_nop 0
	global_load_dwordx4 v[136:139], v[136:137], off offset:224
	s_nop 0
	global_load_dwordx4 v[140:143], v[144:145], off offset:192
	s_nop 0
	global_load_dwordx4 v[144:147], v[144:145], off offset:224
	v_lshl_add_u64 v[148:149], s[14:15], 1, v[52:53]
	v_lshl_add_u64 v[152:153], s[2:3], 1, v[52:53]
	global_load_dwordx4 v[148:151], v[148:149], off
	s_nop 0
	global_load_dwordx4 v[152:155], v[152:153], off
	s_movk_i32 s2, 0x80
	s_lshl_b64 s[14:15], s[2:3], 1
	v_lshl_add_u64 v[240:241], v[50:51], 0, s[14:15]
	v_lshl_add_u64 v[248:249], v[48:49], 0, s[14:15]
	v_lshl_add_u64 v[180:181], v[52:53], 0, s[14:15]
	s_or_b32 s14, s2, 16
	s_mov_b32 s15, s3
	v_lshl_add_u64 v[182:183], s[14:15], 1, v[52:53]
	s_or_b32 s14, s2, 32
	v_lshl_add_u64 v[204:205], s[14:15], 1, v[52:53]
	s_or_b32 s14, s2, 48
	v_lshl_add_u64 v[206:207], s[14:15], 1, v[52:53]
	s_or_b32 s14, s2, 64
	v_lshl_add_u64 v[228:229], s[14:15], 1, v[52:53]
	s_or_b32 s14, s2, 0x50
	v_lshl_add_u64 v[232:233], s[14:15], 1, v[52:53]
	global_load_dwordx4 v[156:159], v[240:241], off
	global_load_dwordx4 v[160:163], v[240:241], off offset:32
	global_load_dwordx4 v[164:167], v[248:249], off
	global_load_dwordx4 v[168:171], v[248:249], off offset:32
	global_load_dwordx4 v[172:175], v[180:181], off
	global_load_dwordx4 v[176:179], v[182:183], off
	s_nop 0
	global_load_dwordx4 v[180:183], v[240:241], off offset:64
	global_load_dwordx4 v[184:187], v[240:241], off offset:96
	global_load_dwordx4 v[188:191], v[248:249], off offset:64
	global_load_dwordx4 v[192:195], v[248:249], off offset:96
	global_load_dwordx4 v[196:199], v[204:205], off
	global_load_dwordx4 v[200:203], v[206:207], off
	s_nop 0
	global_load_dwordx4 v[204:207], v[240:241], off offset:128
	global_load_dwordx4 v[208:211], v[240:241], off offset:160
	global_load_dwordx4 v[220:223], v[248:249], off offset:128
	global_load_dwordx4 v[224:227], v[248:249], off offset:160
	s_nop 0
	global_load_dwordx4 v[228:231], v[228:229], off
	s_nop 0
	global_load_dwordx4 v[232:235], v[232:233], off
	s_or_b32 s14, s2, 0x60
	s_or_b32 s2, s2, 0x70
	global_load_dwordx4 v[236:239], v[240:241], off offset:192
	s_nop 0
	global_load_dwordx4 v[240:243], v[240:241], off offset:224
	s_nop 0
	global_load_dwordx4 v[244:247], v[248:249], off offset:192
	s_nop 0
	global_load_dwordx4 v[248:251], v[248:249], off offset:224
	s_waitcnt vmcnt(22)
	v_mfma_f32_32x32x16_bf16 v[2:17], v[60:63], v[68:71], v[2:17]
	v_mfma_f32_32x32x16_bf16 v[18:33], v[60:63], v[76:79], v[18:33]
	v_mfma_f32_32x32x16_bf16 v[2:17], v[64:67], v[72:75], v[2:17]
	v_mfma_f32_32x32x16_bf16 v[18:33], v[64:67], v[80:83], v[18:33]
	v_mfma_f32_32x32x16_bf16 v[2:17], v[84:87], v[92:95], v[2:17]
	v_mfma_f32_32x32x16_bf16 v[18:33], v[84:87], v[100:103], v[18:33]
	v_mfma_f32_32x32x16_bf16 v[2:17], v[88:91], v[96:99], v[2:17]
	v_mfma_f32_32x32x16_bf16 v[18:33], v[88:91], v[104:107], v[18:33]
	s_mov_b32 s14, 0xe0
	s_mov_b32 s15, s3
	v_lshl_add_u64 v[60:61], s[14:15], 1, v[52:53]
	s_mov_b32 s14, 0xf0
	v_lshl_add_u64 v[64:65], s[14:15], 1, v[52:53]
	global_load_dwordx4 v[60:63], v[60:61], off
	global_load_dwordx4 v[64:67], v[64:65], off
	v_mfma_f32_32x32x16_bf16 v[2:17], v[108:111], v[116:119], v[2:17]
	v_mfma_f32_32x32x16_bf16 v[18:33], v[108:111], v[124:127], v[18:33]
	v_mfma_f32_32x32x16_bf16 v[2:17], v[112:115], v[120:123], v[2:17]
	v_mfma_f32_32x32x16_bf16 v[18:33], v[112:115], v[128:131], v[18:33]
	v_mfma_f32_32x32x16_bf16 v[2:17], v[132:135], v[140:143], v[2:17]
	v_mfma_f32_32x32x16_bf16 v[18:33], v[132:135], v[148:151], v[18:33]
	v_mfma_f32_32x32x16_bf16 v[2:17], v[136:139], v[144:147], v[2:17]
	v_mfma_f32_32x32x16_bf16 v[18:33], v[136:139], v[152:155], v[18:33]
	s_waitcnt vmcnt(2)
; #define MFMA32(a, b, c) __builtin_amdgcn_mfma_f32_32x32x16_bf16(a, b, c, 0, 0, 0)
; #define MFMA32(a, b, c) __builtin_amdgcn_mfma_f32_32x32x16_f16(a, b, c, 0, 0, 0)
; __device__ __forceinline__ void ctx_item(LAS float* L, int item, const f16* hc, const f16* Wssm, f16* X) {
;     ...
;         for (int k = 0; k < 8; ++k) { acc0 = MFMA32(av[k], b0[k], acc0); acc1 = MFMA32(av[k], b1[k], acc1); } }
; #pragma unroll
;     for (int r = 0; r < 16; ++r) { L[((wave * 2 + 0) * 16 + r) * 64 + lane] = acc0[r]; L[((wave * 2 + 1) * 16 + r) * 64 + lane] = acc1[r]; }
;     __syncthreads();
; #pragma unroll
;     for (int i = 0; i < 4; ++i) { const int idx = tid + NTHREADS * i, ln = idx & 63, reg = (idx >> 6) & 15, t = idx >> 10; float sum = 0.f;
; #pragma unroll
;         for (int w = 0; w < 8; ++w) sum += L[((w * 2 + t) * 16 + reg) * 64 + ln];
;         const int row = (reg & 3) + 8 * (reg >> 2) + 4 * (ln >> 5), ch = cb * 64 + t * 32 + (ln & 31);
;         X[(size_t)(ch >> 4) * XGS + (size_t)(NLC + rb) * XK + 256 + row * 16 + (ch & 15)] = (f16)sum; }
;     __syncthreads();
; }
	v_mfma_f32_32x32x16_bf16 v[2:17], v[156:159], v[164:167], v[2:17]
	v_mfma_f32_32x32x16_bf16 v[18:33], v[156:159], v[172:175], v[18:33]
	v_mfma_f32_32x32x16_bf16 v[2:17], v[160:163], v[168:171], v[2:17]
	v_mfma_f32_32x32x16_bf16 v[18:33], v[160:163], v[176:179], v[18:33]
	v_mfma_f32_32x32x16_bf16 v[2:17], v[180:183], v[188:191], v[2:17]
	v_mfma_f32_32x32x16_bf16 v[18:33], v[180:183], v[196:199], v[18:33]
	v_mfma_f32_32x32x16_bf16 v[2:17], v[184:187], v[192:195], v[2:17]
	v_mfma_f32_32x32x16_bf16 v[18:33], v[184:187], v[200:203], v[18:33]
	v_mfma_f32_32x32x16_bf16 v[2:17], v[204:207], v[220:223], v[2:17]
	v_mfma_f32_32x32x16_bf16 v[18:33], v[204:207], v[228:231], v[18:33]
	v_mfma_f32_32x32x16_bf16 v[2:17], v[208:211], v[224:227], v[2:17]
	v_mfma_f32_32x32x16_bf16 v[18:33], v[208:211], v[232:235], v[18:33]
	v_mfma_f32_32x32x16_bf16 v[2:17], v[236:239], v[244:247], v[2:17]
	s_waitcnt vmcnt(1)
	v_mfma_f32_32x32x16_bf16 v[18:33], v[236:239], v[60:63], v[18:33]
	v_mfma_f32_32x32x16_bf16 v[2:17], v[240:243], v[248:251], v[2:17]
	s_waitcnt vmcnt(0)
	v_mfma_f32_32x32x16_bf16 v[18:33], v[240:243], v[64:67], v[18:33]
	s_nop 9
	ds_write2st64_b32 v1, v2, v3 offset1:1
	ds_write2st64_b32 v1, v18, v19 offset0:16 offset1:17
	ds_write2st64_b32 v1, v4, v5 offset0:2 offset1:3
	ds_write2st64_b32 v1, v20, v21 offset0:18 offset1:19
	ds_write2st64_b32 v1, v6, v7 offset0:4 offset1:5
	ds_write2st64_b32 v1, v22, v23 offset0:20 offset1:21
	ds_write2st64_b32 v1, v8, v9 offset0:6 offset1:7
	ds_write2st64_b32 v1, v24, v25 offset0:22 offset1:23
	ds_write2st64_b32 v1, v10, v11 offset0:8 offset1:9
	ds_write2st64_b32 v1, v26, v27 offset0:24 offset1:25
	ds_write2st64_b32 v1, v12, v13 offset0:10 offset1:11
	ds_write2st64_b32 v1, v28, v29 offset0:26 offset1:27
	ds_write2st64_b32 v1, v14, v15 offset0:12 offset1:13
	ds_write2st64_b32 v1, v30, v31 offset0:28 offset1:29
	ds_write2st64_b32 v1, v16, v17 offset0:14 offset1:15
	ds_write2st64_b32 v1, v32, v33 offset0:30 offset1:31
	v_add_u32_e32 v16, v54, v55
	s_waitcnt lgkmcnt(0)
	s_barrier
	ds_read2st64_b32 v[2:3], v16 offset1:16
	ds_read2st64_b32 v[4:5], v16 offset0:32 offset1:48
	ds_read2st64_b32 v[6:7], v16 offset0:64 offset1:80
	s_add_i32 s2, s12, 0x200
	ds_read2st64_b32 v[8:9], v16 offset0:96 offset1:112
	ds_read2st64_b32 v[10:11], v16 offset0:128 offset1:144
	ds_read2st64_b32 v[12:13], v16 offset0:160 offset1:176
	ds_read2st64_b32 v[14:15], v16 offset0:192 offset1:208
	ds_read2st64_b32 v[16:17], v16 offset0:224 offset1:240
	s_waitcnt lgkmcnt(7)
	v_add_f32_e32 v2, 0, v2
	s_waitcnt lgkmcnt(6)
	v_add_f32_e32 v2, v2, v4
	s_waitcnt lgkmcnt(5)
	v_add_f32_e32 v2, v2, v6
	s_mul_hi_i32 s11, s2, 0x600
	s_mulk_i32 s2, 0x600
	s_waitcnt lgkmcnt(4)
	v_add_f32_e32 v2, v2, v8
	s_add_u32 s10, s8, s2
	s_waitcnt lgkmcnt(3)
	v_add_f32_e32 v2, v2, v10
	v_lshrrev_b32_e32 v4, 4, v47
	ds_read2st64_b32 v[22:23], v57 offset1:32
	s_addc_u32 s11, s9, s11
	s_waitcnt lgkmcnt(3)
	v_add_f32_e32 v2, v2, v12
	v_mul_u32_u24_e32 v34, 0xc6000, v4
	s_waitcnt lgkmcnt(2)
	v_add_f32_e32 v2, v2, v14
	v_lshl_add_u64 v[18:19], s[10:11], 0, v[34:35]
	v_mov_b32_e32 v41, v35
	ds_read2st64_b32 v[24:25], v57 offset0:64 offset1:96
	s_waitcnt lgkmcnt(2)
	v_add_f32_e32 v2, v2, v16
	v_lshl_add_u64 v[20:21], v[18:19], 0, v[40:41]
	v_mov_b32_e32 v43, v35
	v_cvt_pk_bf16_f32 v2, v2, s0
	v_lshl_add_u64 v[20:21], v[20:21], 0, v[42:43]
	ds_read2st64_b32 v[26:27], v57 offset0:128 offset1:160
	global_store_short v[20:21], v2, off offset:512
	s_waitcnt lgkmcnt(2)
	v_add_f32_e32 v2, 0, v22
	v_add_f32_e32 v2, v2, v23
	ds_read2st64_b32 v[22:23], v57 offset0:192 offset1:224
	s_waitcnt lgkmcnt(2)
	v_add_f32_e32 v2, v2, v24
	v_add_f32_e32 v2, v2, v25
	s_waitcnt lgkmcnt(1)
	v_add_f32_e32 v2, v2, v26
	v_add_f32_e32 v2, v2, v27
	s_waitcnt lgkmcnt(0)
	v_add_f32_e32 v2, v2, v22
	v_mov_b32_e32 v45, v35
	v_add_f32_e32 v2, v2, v23
	v_lshl_add_u64 v[18:19], v[18:19], 0, v[44:45]
	v_cvt_pk_bf16_f32 v2, v2, s0
	v_lshl_add_u64 v[18:19], v[18:19], 0, v[42:43]
	global_store_short v[18:19], v2, off offset:512
	v_add_f32_e32 v2, 0, v3
	v_add_f32_e32 v2, v2, v5
	v_add_f32_e32 v2, v2, v7
	v_add_f32_e32 v2, v2, v9
	v_add_f32_e32 v2, v2, v11
	v_add_f32_e32 v2, v2, v13
	v_add_f32_e32 v2, v2, v15
	v_add_f32_e32 v2, v2, v17
	v_cvt_pk_bf16_f32 v6, v2, s0
	ds_read2st64_b32 v[2:3], v58 offset1:32
	v_add_co_u32_e32 v4, vcc, s0, v20
	s_add_i32 s1, s1, s17
	s_nop 0
	v_addc_co_u32_e32 v5, vcc, 0, v21, vcc
	global_store_short v[4:5], v6, off offset:512
	ds_read2st64_b32 v[4:5], v58 offset0:64 offset1:96
	ds_read2st64_b32 v[6:7], v58 offset0:128 offset1:160
	s_waitcnt lgkmcnt(2)
	v_add_f32_e32 v2, 0, v2
	v_add_f32_e32 v8, v2, v3
	ds_read2st64_b32 v[2:3], v58 offset0:192 offset1:224
	s_waitcnt lgkmcnt(2)
	v_add_f32_e32 v4, v8, v4
	v_add_f32_e32 v4, v4, v5
	s_waitcnt lgkmcnt(1)
	v_add_f32_e32 v4, v4, v6
	v_add_f32_e32 v4, v4, v7
	s_waitcnt lgkmcnt(0)
	v_add_f32_e32 v2, v4, v2
	v_add_f32_e32 v2, v2, v3
	v_add_u32_e32 v3, 32, v47
	v_cvt_pk_bf16_f32 v4, v2, s0
	v_lshrrev_b32_e32 v2, 4, v3
	v_mul_u32_u24_e32 v34, 0xc6000, v2
	v_lshl_add_u64 v[2:3], s[10:11], 0, v[34:35]
	v_mov_b32_e32 v47, v35
	v_lshl_add_u64 v[2:3], v[2:3], 0, v[46:47]
	v_lshl_add_u64 v[2:3], v[2:3], 0, v[42:43]
	s_cmpk_lt_i32 s1, 0x100
	global_store_short v[2:3], v4, off offset:512
	s_barrier
	s_cbranch_scc1 .LBB0_433
